# P6: older wave-half's alignment barrier moved ~85 instructions into the SwiGLU epilogue so it computes its first block beside the other half's last MFMA segment
# speedup vs baseline: 1.0055x; 1.0055x over previous
; __device__ __forceinline__ float sigmoidf_(float x) { return __builtin_amdgcn_rcpf(1.0f + __expf(-x)); }
; __device__ __forceinline__ u32x4 pack8(f32x4 a, f32x4 b) { u32x4 w; w.x = cvt_pk_bf16(a[0], a[1]); w.y = cvt_pk_bf16(a[2], a[3]); w.z = cvt_pk_bf16(b[0], b[1]); w.w = cvt_pk_bf16(b[2], b[3]); return w; }
; #define PG8_BAR __builtin_amdgcn_s_barrier()
; template <class Epi, class Sched>
; __device__ __forceinline__ void gemm_phase(LAS unsigned char* lds, const Gemm g, const Sched& S, const Epi& E, int tid_in) {
;     ...
;         if (wr == 0) PG8_BAR;
;     __device__ __forceinline__ bool operator()(f32x4 (&acc)[2][2][4][2], const Unit& u, int wr, int wc, int fr, int fq) const {
;         const int row0 = u.pm * BM + wr * 64 + fr, col0 = u.pn * HALF + wc * 32 + 8 * fq;
; #pragma unroll
;         for (int ai = 0; ai < 2; ++ai)
; #pragma unroll
;             for (int m = 0; m < 4; ++m) {
;                 f32x4 v[2];
; #pragma unroll
;                 for (int n = 0; n < 2; ++n)
; #pragma unroll
;                     for (int i = 0; i < 4; ++i) { const float gx = acc[ai][0][m][n][i]; v[n][i] = gx * sigmoidf_(gx) * acc[ai][1][m][n][i]; }
;                 *(u32x4*)(O + (size_t)(row0 + ai * HALF + m * 16) * DFF + col0) = pack8(v[0], v[1]);
.Lpeel_exit_2:
.LBB0_766:
	v_mul_f32_e32 v145, 0xbfb8aa3b, v124
	v_exp_f32_e32 v145, v145
	v_mul_f32_e32 v146, 0xbfb8aa3b, v125
	v_exp_f32_e32 v147, v146
	v_lshl_or_b32 v146, s47, 7, v150
	v_add_f32_e32 v145, 1.0, v145
	v_rcp_f32_e32 v145, v145
	v_add_f32_e32 v147, 1.0, v147
	v_rcp_f32_e32 v154, v147
	v_lshl_add_u32 v144, s26, 8, v148
	v_mul_f32_e32 v124, v124, v145
	v_mul_f32_e32 v116, v124, v116
	v_mul_f32_e32 v124, v125, v154
	v_mul_f32_e32 v125, 0xbfb8aa3b, v126
	v_exp_f32_e32 v125, v125
	v_mul_f32_e32 v145, 0xbfb8aa3b, v127
	v_exp_f32_e32 v145, v145
	v_mul_f32_e32 v117, v124, v117
	v_add_f32_e32 v124, 1.0, v125
	v_rcp_f32_e32 v124, v124
	v_add_f32_e32 v125, 1.0, v145
	v_mul_f32_e32 v145, 0xbfb8aa3b, v120
	v_rcp_f32_e32 v125, v125
	v_exp_f32_e32 v145, v145
	v_mul_f32_e32 v124, v126, v124
	v_mul_f32_e32 v118, v124, v118
	v_mul_f32_e32 v124, v127, v125
	v_add_f32_e32 v125, 1.0, v145
	v_rcp_f32_e32 v125, v125
	v_mul_f32_e32 v126, 0xbfb8aa3b, v121
	v_exp_f32_e32 v126, v126
	v_mul_f32_e32 v119, v124, v119
	v_mul_f32_e32 v120, v120, v125
	v_mul_f32_e32 v112, v120, v112
	v_add_f32_e32 v120, 1.0, v126
	v_mul_f32_e32 v124, 0xbfb8aa3b, v122
	v_rcp_f32_e32 v120, v120
	v_exp_f32_e32 v124, v124
	v_mul_f32_e32 v125, 0xbfb8aa3b, v123
	v_exp_f32_e32 v125, v125
	v_mul_f32_e32 v120, v121, v120
	v_add_f32_e32 v121, 1.0, v124
	v_rcp_f32_e32 v121, v121
	v_add_f32_e32 v124, 1.0, v125
	v_rcp_f32_e32 v124, v124
	v_mul_f32_e32 v113, v120, v113
	v_mul_f32_e32 v120, v122, v121
	v_mul_f32_e32 v122, 0xbfb8aa3b, v108
	v_mul_f32_e32 v114, v120, v114
	v_mul_f32_e32 v120, v123, v124
	v_exp_f32_e32 v122, v122
	v_mul_f32_e32 v123, 0xbfb8aa3b, v109
	v_exp_f32_e32 v123, v123
	v_ashrrev_i32_e32 v147, 31, v146
	v_add_f32_e32 v122, 1.0, v122
	v_rcp_f32_e32 v122, v122
	v_add_f32_e32 v123, 1.0, v123
	v_rcp_f32_e32 v123, v123
	v_mul_f32_e32 v115, v120, v115
	v_cvt_pk_bf16_f32 v116, v116, v117
	v_cvt_pk_bf16_f32 v117, v118, v119
	v_cvt_pk_bf16_f32 v118, v112, v113
	v_mov_b64_e32 v[112:113], s[12:13]
	v_cvt_pk_bf16_f32 v119, v114, v115
	v_mad_i64_i32 v[120:121], s[28:29], v144, s46, v[112:113]
	v_lshlrev_b64 v[114:115], 1, v[146:147]
	v_mul_f32_e32 v108, v108, v122
	v_lshl_add_u64 v[120:121], v[120:121], 0, v[114:115]
	v_mul_f32_e32 v100, v108, v100
	v_mul_f32_e32 v108, v109, v123
	v_mul_f32_e32 v109, 0xbfb8aa3b, v110
	global_store_dwordx4 v[120:121], v[116:119], off
	v_exp_f32_e32 v109, v109
	v_mul_f32_e32 v101, v108, v101
	v_mul_f32_e32 v116, 0xbfb8aa3b, v111
	v_exp_f32_e32 v116, v116
	v_add_f32_e32 v108, 1.0, v109
	v_rcp_f32_e32 v108, v108
	s_and_b64 vcc, exec, s[16:17]
	s_cbranch_vccz .Lp6_align_skip
	s_barrier
.Lp6_align_skip:
	s_andn2_b64 vcc, exec, s[4:5]
	v_add_f32_e32 v109, 1.0, v116
	v_mul_f32_e32 v116, 0xbfb8aa3b, v104
	v_rcp_f32_e32 v109, v109
	v_exp_f32_e32 v116, v116
	v_mul_f32_e32 v108, v110, v108
	v_mul_f32_e32 v102, v108, v102
	v_mul_f32_e32 v108, v111, v109
	v_add_f32_e32 v109, 1.0, v116
	v_rcp_f32_e32 v109, v109
	v_mul_f32_e32 v110, 0xbfb8aa3b, v105
	v_exp_f32_e32 v110, v110
	v_mul_f32_e32 v103, v108, v103
	v_mul_f32_e32 v104, v104, v109
	v_mul_f32_e32 v104, v104, v96
	v_add_f32_e32 v96, 1.0, v110
	v_mul_f32_e32 v108, 0xbfb8aa3b, v106
	v_rcp_f32_e32 v96, v96
	v_exp_f32_e32 v108, v108
	v_mul_f32_e32 v109, 0xbfb8aa3b, v107
	v_exp_f32_e32 v109, v109
	v_mul_f32_e32 v96, v105, v96
	v_add_f32_e32 v105, 1.0, v108
	v_rcp_f32_e32 v105, v105
	v_add_f32_e32 v108, 1.0, v109
	v_rcp_f32_e32 v108, v108
	v_mul_f32_e32 v109, v96, v97
	v_mul_f32_e32 v96, v106, v105
	v_mul_f32_e32 v105, v96, v98
	v_mul_f32_e32 v96, v107, v108
	v_mul_f32_e32 v99, v96, v99
	v_cvt_pk_bf16_f32 v96, v100, v101
	v_cvt_pk_bf16_f32 v97, v102, v103
	v_mul_f32_e32 v102, 0xbfb8aa3b, v92
	v_exp_f32_e32 v102, v102
	v_mul_f32_e32 v103, 0xbfb8aa3b, v93
	v_exp_f32_e32 v103, v103
	v_or_b32_e32 v100, 16, v144
	v_add_f32_e32 v102, 1.0, v102
	v_rcp_f32_e32 v102, v102
	v_add_f32_e32 v103, 1.0, v103
	v_rcp_f32_e32 v103, v103
	v_mad_i64_i32 v[100:101], s[28:29], v100, s46, v[112:113]
	v_mul_f32_e32 v92, v92, v102
	v_lshl_add_u64 v[100:101], v[100:101], 0, v[114:115]
	v_mul_f32_e32 v84, v92, v84
	v_mul_f32_e32 v92, v93, v103
	v_mul_f32_e32 v93, 0xbfb8aa3b, v94
	v_cvt_pk_bf16_f32 v98, v104, v109
	v_cvt_pk_bf16_f32 v99, v105, v99
	global_store_dwordx4 v[100:101], v[96:99], off
	v_exp_f32_e32 v93, v93
	v_mul_f32_e32 v85, v92, v85
	v_mul_f32_e32 v96, 0xbfb8aa3b, v95
	v_exp_f32_e32 v96, v96
	v_add_f32_e32 v92, 1.0, v93
	v_rcp_f32_e32 v92, v92
	s_mov_b64 s[4:5], -1
	v_add_f32_e32 v93, 1.0, v96
	v_mul_f32_e32 v96, 0xbfb8aa3b, v88
	v_rcp_f32_e32 v93, v93
	v_exp_f32_e32 v96, v96
	v_mul_f32_e32 v92, v94, v92
	v_mul_f32_e32 v86, v92, v86
	v_mul_f32_e32 v92, v95, v93
	v_add_f32_e32 v93, 1.0, v96
	v_rcp_f32_e32 v93, v93
	v_mul_f32_e32 v94, 0xbfb8aa3b, v89
	v_exp_f32_e32 v94, v94
	v_mul_f32_e32 v87, v92, v87
	v_mul_f32_e32 v88, v88, v93
	v_mul_f32_e32 v88, v88, v80
	v_add_f32_e32 v80, 1.0, v94
	v_mul_f32_e32 v92, 0xbfb8aa3b, v90
	v_rcp_f32_e32 v80, v80
	v_exp_f32_e32 v92, v92
	v_mul_f32_e32 v93, 0xbfb8aa3b, v91
	v_exp_f32_e32 v93, v93
	v_mul_f32_e32 v80, v89, v80
	v_add_f32_e32 v89, 1.0, v92
	v_rcp_f32_e32 v89, v89
	v_add_f32_e32 v92, 1.0, v93
	v_rcp_f32_e32 v92, v92
	v_mul_f32_e32 v93, v80, v81
	v_mul_f32_e32 v80, v90, v89
	v_mul_f32_e32 v89, v80, v82
	v_mul_f32_e32 v80, v91, v92
	v_mul_f32_e32 v83, v80, v83
	v_cvt_pk_bf16_f32 v80, v84, v85
	v_cvt_pk_bf16_f32 v81, v86, v87
	v_mul_f32_e32 v86, 0xbfb8aa3b, v76
	v_exp_f32_e32 v86, v86
	v_mul_f32_e32 v87, 0xbfb8aa3b, v77
	v_exp_f32_e32 v87, v87
	v_or_b32_e32 v84, 32, v144
	v_add_f32_e32 v86, 1.0, v86
	v_rcp_f32_e32 v86, v86
	v_add_f32_e32 v87, 1.0, v87
	v_rcp_f32_e32 v87, v87
; __device__ __forceinline__ float sigmoidf_(float x) { return __builtin_amdgcn_rcpf(1.0f + __expf(-x)); }
; __device__ __forceinline__ u32x4 pack8(f32x4 a, f32x4 b) { u32x4 w; w.x = cvt_pk_bf16(a[0], a[1]); w.y = cvt_pk_bf16(a[2], a[3]); w.z = cvt_pk_bf16(b[0], b[1]); w.w = cvt_pk_bf16(b[2], b[3]); return w; }
;     __device__ __forceinline__ bool operator()(f32x4 (&acc)[2][2][4][2], const Unit& u, int wr, int wc, int fr, int fq) const {
;     ...
;         for (int ai = 0; ai < 2; ++ai)
; #pragma unroll
;             for (int m = 0; m < 4; ++m) {
;                 f32x4 v[2];
; #pragma unroll
;                 for (int n = 0; n < 2; ++n)
; #pragma unroll
;                     for (int i = 0; i < 4; ++i) { const float gx = acc[ai][0][m][n][i]; v[n][i] = gx * sigmoidf_(gx) * acc[ai][1][m][n][i]; }
;                 *(u32x4*)(O + (size_t)(row0 + ai * HALF + m * 16) * DFF + col0) = pack8(v[0], v[1]);
	v_mad_i64_i32 v[84:85], s[28:29], v84, s46, v[112:113]
	v_mul_f32_e32 v76, v76, v86
	v_lshl_add_u64 v[84:85], v[84:85], 0, v[114:115]
	v_mul_f32_e32 v68, v76, v68
	v_mul_f32_e32 v76, v77, v87
	v_mul_f32_e32 v77, 0xbfb8aa3b, v78
	v_cvt_pk_bf16_f32 v82, v88, v93
	v_cvt_pk_bf16_f32 v83, v89, v83
	global_store_dwordx4 v[84:85], v[80:83], off
	v_exp_f32_e32 v77, v77
	v_mul_f32_e32 v69, v76, v69
	v_mul_f32_e32 v80, 0xbfb8aa3b, v79
	v_exp_f32_e32 v80, v80
	v_add_f32_e32 v76, 1.0, v77
	v_rcp_f32_e32 v76, v76
	v_add_f32_e32 v77, 1.0, v80
	v_mul_f32_e32 v80, 0xbfb8aa3b, v72
	v_rcp_f32_e32 v77, v77
	v_exp_f32_e32 v80, v80
	v_mul_f32_e32 v76, v78, v76
	v_mul_f32_e32 v70, v76, v70
	v_mul_f32_e32 v76, v79, v77
	v_add_f32_e32 v77, 1.0, v80
	v_rcp_f32_e32 v77, v77
	v_mul_f32_e32 v78, 0xbfb8aa3b, v73
	v_exp_f32_e32 v78, v78
	v_mul_f32_e32 v71, v76, v71
	v_mul_f32_e32 v72, v72, v77
	v_mul_f32_e32 v72, v72, v64
	v_add_f32_e32 v64, 1.0, v78
	v_mul_f32_e32 v76, 0xbfb8aa3b, v74
	v_rcp_f32_e32 v64, v64
	v_exp_f32_e32 v76, v76
	v_mul_f32_e32 v77, 0xbfb8aa3b, v75
	v_exp_f32_e32 v77, v77
	v_mul_f32_e32 v64, v73, v64
	v_add_f32_e32 v73, 1.0, v76
	v_rcp_f32_e32 v73, v73
	v_add_f32_e32 v76, 1.0, v77
	v_rcp_f32_e32 v76, v76
	v_mul_f32_e32 v77, v64, v65
	v_mul_f32_e32 v64, v74, v73
	v_mul_f32_e32 v73, v64, v66
	v_mul_f32_e32 v64, v75, v76
	v_mul_f32_e32 v67, v64, v67
	v_cvt_pk_bf16_f32 v64, v68, v69
	v_cvt_pk_bf16_f32 v65, v70, v71
	v_mul_f32_e32 v70, 0xbfb8aa3b, v60
	v_exp_f32_e32 v70, v70
	v_mul_f32_e32 v71, 0xbfb8aa3b, v61
	v_or_b32_e32 v68, 48, v144
	v_exp_f32_e32 v71, v71
	v_mad_i64_i32 v[68:69], s[28:29], v68, s46, v[112:113]
	v_lshl_add_u64 v[68:69], v[68:69], 0, v[114:115]
	v_cvt_pk_bf16_f32 v66, v72, v77
	v_cvt_pk_bf16_f32 v67, v73, v67
	global_store_dwordx4 v[68:69], v[64:67], off
	s_nop 1
	v_add_f32_e32 v64, 1.0, v70
	v_rcp_f32_e32 v64, v64
	v_add_f32_e32 v65, 1.0, v71
	v_rcp_f32_e32 v65, v65
	v_add_u32_e32 v66, 0x80, v144
	v_mul_f32_e32 v60, v60, v64
	v_mul_f32_e32 v52, v60, v52
	v_mul_f32_e32 v60, v61, v65
	v_mul_f32_e32 v61, 0xbfb8aa3b, v62
	v_exp_f32_e32 v61, v61
	v_mul_f32_e32 v64, 0xbfb8aa3b, v63
	v_exp_f32_e32 v64, v64
	v_mul_f32_e32 v53, v60, v53
	v_add_f32_e32 v60, 1.0, v61
	v_rcp_f32_e32 v60, v60
	v_add_f32_e32 v61, 1.0, v64
	v_mul_f32_e32 v64, 0xbfb8aa3b, v56
	v_rcp_f32_e32 v61, v61
	v_exp_f32_e32 v64, v64
	v_mul_f32_e32 v60, v62, v60
	v_mul_f32_e32 v54, v60, v54
	v_mul_f32_e32 v60, v63, v61
	v_add_f32_e32 v61, 1.0, v64
	v_rcp_f32_e32 v61, v61
	v_mul_f32_e32 v62, 0xbfb8aa3b, v57
	v_exp_f32_e32 v62, v62
	v_mul_f32_e32 v55, v60, v55
	v_mul_f32_e32 v56, v56, v61
	v_mul_f32_e32 v56, v56, v48
	v_add_f32_e32 v48, 1.0, v62
	v_mul_f32_e32 v60, 0xbfb8aa3b, v58
	v_rcp_f32_e32 v48, v48
	v_exp_f32_e32 v60, v60
	v_mul_f32_e32 v61, 0xbfb8aa3b, v59
	v_exp_f32_e32 v61, v61
	v_mul_f32_e32 v48, v57, v48
	v_add_f32_e32 v57, 1.0, v60
	v_rcp_f32_e32 v57, v57
	v_add_f32_e32 v60, 1.0, v61
	v_rcp_f32_e32 v60, v60
	v_mul_f32_e32 v61, v48, v49
	v_mul_f32_e32 v48, v58, v57
	v_mul_f32_e32 v57, v48, v50
	v_mul_f32_e32 v48, v59, v60
	v_mul_f32_e32 v51, v48, v51
	v_cvt_pk_bf16_f32 v48, v52, v53
	v_cvt_pk_bf16_f32 v49, v54, v55
	v_mul_f32_e32 v54, 0xbfb8aa3b, v44
	v_exp_f32_e32 v54, v54
	v_mul_f32_e32 v55, 0xbfb8aa3b, v45
	v_exp_f32_e32 v55, v55
	v_mad_i64_i32 v[52:53], s[28:29], v66, s46, v[112:113]
	v_add_f32_e32 v54, 1.0, v54
	v_rcp_f32_e32 v54, v54
	v_add_f32_e32 v55, 1.0, v55
	v_rcp_f32_e32 v55, v55
	v_lshl_add_u64 v[52:53], v[52:53], 0, v[114:115]
	v_mul_f32_e32 v44, v44, v54
	v_mul_f32_e32 v36, v44, v36
	v_mul_f32_e32 v44, v45, v55
	v_mul_f32_e32 v45, 0xbfb8aa3b, v46
	v_cvt_pk_bf16_f32 v50, v56, v61
	v_cvt_pk_bf16_f32 v51, v57, v51
	global_store_dwordx4 v[52:53], v[48:51], off
	v_exp_f32_e32 v45, v45
	v_mul_f32_e32 v37, v44, v37
	v_mul_f32_e32 v48, 0xbfb8aa3b, v47
	v_exp_f32_e32 v48, v48
	v_add_f32_e32 v44, 1.0, v45
	v_rcp_f32_e32 v44, v44
	v_add_f32_e32 v45, 1.0, v48
	v_mul_f32_e32 v48, 0xbfb8aa3b, v40
	v_rcp_f32_e32 v45, v45
	v_exp_f32_e32 v48, v48
	v_mul_f32_e32 v44, v46, v44
	v_mul_f32_e32 v38, v44, v38
	v_mul_f32_e32 v44, v47, v45
	v_add_f32_e32 v45, 1.0, v48
	v_rcp_f32_e32 v45, v45
	v_mul_f32_e32 v46, 0xbfb8aa3b, v41
	v_exp_f32_e32 v46, v46
	v_mul_f32_e32 v39, v44, v39
; __device__ __forceinline__ float sigmoidf_(float x) { return __builtin_amdgcn_rcpf(1.0f + __expf(-x)); }
; __device__ __forceinline__ u32x4 pack8(f32x4 a, f32x4 b) { u32x4 w; w.x = cvt_pk_bf16(a[0], a[1]); w.y = cvt_pk_bf16(a[2], a[3]); w.z = cvt_pk_bf16(b[0], b[1]); w.w = cvt_pk_bf16(b[2], b[3]); return w; }
; #define PG8_BAR __builtin_amdgcn_s_barrier()
; template <class Epi, class Sched>
; __device__ __forceinline__ void gemm_phase(LAS unsigned char* lds, const Gemm g, const Sched& S, const Epi& E, int tid_in) {
;     ...
;         if (!has_next) break;
;         if (!keep) {
; #pragma unroll
;             for (int a = 0; a < 2; ++a)
; #pragma unroll
;                 for (int b = 0; b < 2; ++b)
; #pragma unroll
;                     for (int m = 0; m < 4; ++m)
; #pragma unroll
;                         for (int n = 0; n < 2; ++n) acc[a][b][m][n] = (f32x4){0.f, 0.f, 0.f, 0.f};
;         }
;         cur = nxt; cA = nA; cB = nB; ++ui;
;         if (wr == 1) PG8_BAR;
;     __device__ __forceinline__ bool operator()(f32x4 (&acc)[2][2][4][2], const Unit& u, int wr, int wc, int fr, int fq) const {
;     ...
;         for (int ai = 0; ai < 2; ++ai)
; #pragma unroll
;             for (int m = 0; m < 4; ++m) {
;                 f32x4 v[2];
; #pragma unroll
;                 for (int n = 0; n < 2; ++n)
; #pragma unroll
;                     for (int i = 0; i < 4; ++i) { const float gx = acc[ai][0][m][n][i]; v[n][i] = gx * sigmoidf_(gx) * acc[ai][1][m][n][i]; }
;                 *(u32x4*)(O + (size_t)(row0 + ai * HALF + m * 16) * DFF + col0) = pack8(v[0], v[1]);
	v_mul_f32_e32 v40, v40, v45
	v_mul_f32_e32 v40, v40, v32
	v_add_f32_e32 v32, 1.0, v46
	v_mul_f32_e32 v44, 0xbfb8aa3b, v42
	v_rcp_f32_e32 v32, v32
	v_exp_f32_e32 v44, v44
	v_mul_f32_e32 v45, 0xbfb8aa3b, v43
	v_exp_f32_e32 v45, v45
	v_mul_f32_e32 v32, v41, v32
	v_add_f32_e32 v41, 1.0, v44
	v_rcp_f32_e32 v41, v41
	v_add_f32_e32 v44, 1.0, v45
	v_rcp_f32_e32 v44, v44
	v_mul_f32_e32 v45, v32, v33
	v_mul_f32_e32 v32, v42, v41
	v_mul_f32_e32 v41, v32, v34
	v_mul_f32_e32 v32, v43, v44
	v_mul_f32_e32 v35, v32, v35
	v_cvt_pk_bf16_f32 v32, v36, v37
	v_cvt_pk_bf16_f32 v33, v38, v39
	v_mul_f32_e32 v38, 0xbfb8aa3b, v28
	v_exp_f32_e32 v38, v38
	v_mul_f32_e32 v39, 0xbfb8aa3b, v29
	v_exp_f32_e32 v39, v39
	v_add_u32_e32 v36, 0x90, v144
	v_add_f32_e32 v38, 1.0, v38
	v_rcp_f32_e32 v38, v38
	v_add_f32_e32 v39, 1.0, v39
	v_rcp_f32_e32 v39, v39
	v_mad_i64_i32 v[36:37], s[28:29], v36, s46, v[112:113]
	v_mul_f32_e32 v28, v28, v38
	v_lshl_add_u64 v[36:37], v[36:37], 0, v[114:115]
	v_mul_f32_e32 v20, v28, v20
	v_mul_f32_e32 v28, v29, v39
	v_mul_f32_e32 v29, 0xbfb8aa3b, v30
	v_cvt_pk_bf16_f32 v34, v40, v45
	v_cvt_pk_bf16_f32 v35, v41, v35
	global_store_dwordx4 v[36:37], v[32:35], off
	v_exp_f32_e32 v29, v29
	v_mul_f32_e32 v21, v28, v21
	v_mul_f32_e32 v32, 0xbfb8aa3b, v31
	v_exp_f32_e32 v32, v32
	v_add_f32_e32 v28, 1.0, v29
	v_rcp_f32_e32 v28, v28
	v_add_f32_e32 v29, 1.0, v32
	v_mul_f32_e32 v32, 0xbfb8aa3b, v24
	v_rcp_f32_e32 v29, v29
	v_exp_f32_e32 v32, v32
	v_mul_f32_e32 v28, v30, v28
	v_mul_f32_e32 v22, v28, v22
	v_mul_f32_e32 v28, v31, v29
	v_add_f32_e32 v29, 1.0, v32
	v_rcp_f32_e32 v29, v29
	v_mul_f32_e32 v30, 0xbfb8aa3b, v25
	v_exp_f32_e32 v30, v30
	v_mul_f32_e32 v23, v28, v23
	v_mul_f32_e32 v24, v24, v29
	v_mul_f32_e32 v24, v24, v16
	v_add_f32_e32 v16, 1.0, v30
	v_mul_f32_e32 v28, 0xbfb8aa3b, v26
	v_rcp_f32_e32 v16, v16
	v_exp_f32_e32 v28, v28
	v_mul_f32_e32 v29, 0xbfb8aa3b, v27
	v_exp_f32_e32 v29, v29
	v_mul_f32_e32 v16, v25, v16
	v_add_f32_e32 v25, 1.0, v28
	v_rcp_f32_e32 v25, v25
	v_add_f32_e32 v28, 1.0, v29
	v_rcp_f32_e32 v28, v28
	v_mul_f32_e32 v29, v16, v17
	v_mul_f32_e32 v16, v26, v25
	v_mul_f32_e32 v25, v16, v18
	v_mul_f32_e32 v16, v27, v28
	v_mul_f32_e32 v19, v16, v19
	v_cvt_pk_bf16_f32 v16, v20, v21
	v_cvt_pk_bf16_f32 v17, v22, v23
	v_mul_f32_e32 v22, 0xbfb8aa3b, v12
	v_exp_f32_e32 v22, v22
	v_mul_f32_e32 v23, 0xbfb8aa3b, v13
	v_exp_f32_e32 v23, v23
	v_add_u32_e32 v20, 0xa0, v144
	v_add_f32_e32 v22, 1.0, v22
	v_rcp_f32_e32 v22, v22
	v_add_f32_e32 v23, 1.0, v23
	v_rcp_f32_e32 v23, v23
	v_mad_i64_i32 v[20:21], s[28:29], v20, s46, v[112:113]
	v_mul_f32_e32 v12, v12, v22
	v_lshl_add_u64 v[20:21], v[20:21], 0, v[114:115]
	v_mul_f32_e32 v4, v12, v4
	v_mul_f32_e32 v12, v13, v23
	v_mul_f32_e32 v13, 0xbfb8aa3b, v14
	v_cvt_pk_bf16_f32 v18, v24, v29
	v_cvt_pk_bf16_f32 v19, v25, v19
	global_store_dwordx4 v[20:21], v[16:19], off
	v_exp_f32_e32 v13, v13
	v_mul_f32_e32 v5, v12, v5
	v_mul_f32_e32 v16, 0xbfb8aa3b, v15
	v_exp_f32_e32 v16, v16
	v_add_f32_e32 v12, 1.0, v13
	v_rcp_f32_e32 v12, v12
	v_add_f32_e32 v13, 1.0, v16
	v_mul_f32_e32 v16, 0xbfb8aa3b, v8
	v_rcp_f32_e32 v13, v13
	v_exp_f32_e32 v16, v16
	v_mul_f32_e32 v12, v14, v12
	v_mul_f32_e32 v6, v12, v6
	v_mul_f32_e32 v12, v15, v13
	v_add_f32_e32 v13, 1.0, v16
	v_rcp_f32_e32 v13, v13
	v_mul_f32_e32 v14, 0xbfb8aa3b, v9
	v_exp_f32_e32 v14, v14
	v_mul_f32_e32 v7, v12, v7
	v_mul_f32_e32 v8, v8, v13
	v_mul_f32_e32 v8, v8, v0
	v_add_f32_e32 v0, 1.0, v14
	v_mul_f32_e32 v12, 0xbfb8aa3b, v10
	v_rcp_f32_e32 v0, v0
	v_exp_f32_e32 v12, v12
	v_mul_f32_e32 v13, 0xbfb8aa3b, v11
	v_exp_f32_e32 v13, v13
	v_mul_f32_e32 v0, v9, v0
	v_add_f32_e32 v9, 1.0, v12
	v_rcp_f32_e32 v9, v9
	v_add_f32_e32 v12, 1.0, v13
	v_rcp_f32_e32 v12, v12
	v_mul_f32_e32 v13, v0, v1
	v_mul_f32_e32 v0, v10, v9
	v_mul_f32_e32 v9, v0, v2
	v_mul_f32_e32 v0, v11, v12
	v_mul_f32_e32 v3, v0, v3
	v_cvt_pk_bf16_f32 v0, v4, v5
	v_add_u32_e32 v4, 0xb0, v144
	v_mad_i64_i32 v[4:5], s[28:29], v4, s46, v[112:113]
	v_lshl_add_u64 v[4:5], v[4:5], 0, v[114:115]
	v_cvt_pk_bf16_f32 v1, v6, v7
	v_cvt_pk_bf16_f32 v2, v8, v13
	v_cvt_pk_bf16_f32 v3, v9, v3
	global_store_dwordx4 v[4:5], v[0:3], off
	s_cbranch_vccnz .LBB0_759
	s_andn2_b64 vcc, exec, s[6:7]
	s_cbranch_vccnz .LBB0_758
	s_barrier
	s_branch .LBB0_758
